# v89 + BCV tile header: 3 dead kernarg spill reloads removed (CFG-liveness checked)
# baseline (speedup 1.0000x reference)
; template <class Epi, bool ALIGN_EPI = PG8_ALIGN, bool SP2 = PG8_SP2>
; __device__ __forceinline__ void gemm_phase(LAS uchar* lds, const Gemm g, const StaticOrder& S, const Epi& E) {
;     ...
;         const bool has_next = S.next(ui + 1, nxt);
;         const char* nA = has_next ? (const char*)g.A + (size_t)nxt.pm * tstepA : cA; const char* nB = has_next ? (const char*)g.Bt + (size_t)nxt.pn * tstepB : cB;
.LBB0_664:
	s_andn2_b64 s[0:1], exec, s[4:5]
	s_andn2_b64 vcc, exec, s[4:5]
	s_mov_b64 s[4:5], s[12:13]
	s_cbranch_vccnz .LBB0_666
	s_mul_i32 s4, s31, 0x88000
	v_readlane_b32 s40, v254, 4
	s_mul_hi_i32 s5, s31, 0x88000
	v_readlane_b32 s41, v254, 5
	s_add_u32 s4, s40, s4
	s_addc_u32 s5, s41, s5
	v_readlane_b32 s39, v254, 3
	v_readlane_b32 s42, v254, 6
	v_readlane_b32 s43, v254, 7
